# q7 plus poll back-off in the grid-barrier spin loops (s_sleep 1 -> 3)
# speedup vs baseline: 1.0109x; 1.0109x over previous
; __global__ void __launch_bounds__(512) hybrid_fwd(Params p) {
;     ...
;         if (p.ws == nullptr) grid.sync();
.LBB0_88:
	s_sleep 3
	global_load_dword v1, v193, s[42:43] offset:32 sc1
	s_waitcnt vmcnt(0)
	v_and_b32_e32 v1, 0xffff0000, v1
	v_cmp_ne_u32_e32 vcc, v1, v0
	s_or_b64 s[48:49], vcc, s[48:49]
	s_andn2_b64 exec, exec, s[48:49]
	s_cbranch_execnz .LBB0_88

; __device__ __forceinline__ unsigned xb_ld(unsigned* p)              { return __hip_atomic_load(p, __ATOMIC_RELAXED, __HIP_MEMORY_SCOPE_AGENT); }
; __device__ __forceinline__ void xcd_barrier_complete(unsigned* bar, unsigned x, unsigned& nloc, unsigned& nx) {
;     const unsigned G = gridDim.x * gridDim.y * gridDim.z;
;     unsigned sum, cnt, mine, sp = 0u;
;     for (;;) {
;         sum = 0u; cnt = 0u; mine = 0u;
; #pragma unroll
;         for (unsigned j = 0; j < 16; ++j) { const unsigned c = xb_ld(&bar[XB_XCNT(j)]); sum += c; cnt += (c > 0u) ? 1u : 0u; mine = (j == x) ? c : mine; }
;         if (sum == G) break;
;         __builtin_amdgcn_s_sleep(1);
;         if ((++sp & 255u) == 0u) { if (xb_ld(&bar[XB_TMO])) break; if (sp > XB_SPIN_CAP) { atomicAdd(&bar[XB_TMO], 1u); break; } }
;     }
;     nloc = mine > 0u ? mine : 1u; nx = cnt > 0u ? cnt : 1u;
; }
.LBB0_95:
	s_waitcnt lgkmcnt(0)
	global_load_dword v0, v193, s[58:59] sc1
	global_load_dword v1, v193, s[58:59] offset:256 sc1
	global_load_dword v2, v193, s[58:59] offset:512 sc1
	global_load_dword v3, v193, s[58:59] offset:768 sc1
	global_load_dword v4, v193, s[58:59] offset:1024 sc1
	global_load_dword v5, v193, s[58:59] offset:1280 sc1
	global_load_dword v6, v193, s[58:59] offset:1536 sc1
	global_load_dword v7, v193, s[58:59] offset:1792 sc1
	global_load_dword v8, v193, s[58:59] offset:2048 sc1
	global_load_dword v9, v193, s[58:59] offset:2304 sc1
	global_load_dword v10, v193, s[58:59] offset:2560 sc1
	global_load_dword v11, v193, s[58:59] offset:2816 sc1
	global_load_dword v12, v193, s[58:59] offset:3072 sc1
	global_load_dword v13, v193, s[58:59] offset:3328 sc1
	global_load_dword v14, v193, s[58:59] offset:3584 sc1
	global_load_dword v15, v193, s[58:59] offset:3840 sc1
	s_mov_b64 s[42:43], -1
	s_mov_b64 s[48:49], -1
	s_waitcnt vmcnt(0)
	v_add_u32_e32 v16, v1, v0
	v_add_u32_e32 v16, v16, v2
	v_add_u32_e32 v16, v16, v3
	v_add_u32_e32 v16, v16, v4
	v_add_u32_e32 v16, v16, v5
	v_add_u32_e32 v16, v16, v6
	v_add_u32_e32 v16, v16, v7
	v_add_u32_e32 v16, v16, v8
	v_add_u32_e32 v16, v16, v9
	v_add_u32_e32 v16, v16, v10
	v_add_u32_e32 v16, v16, v11
	v_add_u32_e32 v16, v16, v12
	v_add_u32_e32 v16, v16, v13
	v_add_u32_e32 v16, v16, v14
	v_add_u32_e32 v16, v16, v15
	v_cmp_eq_u32_e32 vcc, s95, v16
	s_cbranch_vccnz .LBB0_94
	s_and_b32 s20, s19, 0xff
	s_cmp_eq_u32 s20, 0
	s_mov_b64 s[50:51], -1
	s_sleep 3
	s_cbranch_scc1 .LBB0_99
	s_and_b64 vcc, exec, s[50:51]
	s_cbranch_vccz .LBB0_94

; __device__ __forceinline__ unsigned xb_ld(unsigned* p)              { return __hip_atomic_load(p, __ATOMIC_RELAXED, __HIP_MEMORY_SCOPE_AGENT); }
; __device__ __forceinline__ unsigned xb_add(unsigned* p, unsigned v) { return __hip_atomic_fetch_add(p, v, __ATOMIC_RELAXED, __HIP_MEMORY_SCOPE_AGENT); }
; #define XB_SPIN(cond, bar) do { unsigned _sp = 0; while (cond) { __builtin_amdgcn_s_sleep(1); \
;     if ((++_sp & 255u) == 0u) { if (xb_ld(&(bar)[XB_TMO])) break; if (_sp > XB_SPIN_CAP) { atomicAdd(&(bar)[XB_TMO], 1u); break; } } } } while (0)
; __device__ __forceinline__ void xcd_barrier(const XcdBarrier& b) {
;     ...
;             else XB_SPIN(xb_ld(&bar[XB_TOPGEN]) == tg, bar);
;             __builtin_amdgcn_fence(__ATOMIC_ACQUIRE, "agent");
;             xb_add(&bar[XB_XGEN(b.x)], 1u);
;             asm volatile("s_waitcnt vmcnt(0)" ::: "memory");
;         } else {
;             XB_SPIN(xb_ld(&bar[XB_XGEN(b.x)]) == gen, bar);
.LBB0_113:
	s_and_b32 s20, s19, 0xff
	s_mov_b64 s[54:55], -1
	s_cmp_lg_u32 s20, 0
	s_mov_b64 s[60:61], -1
	s_sleep 3
	s_cbranch_scc0 .LBB0_116
	s_and_b64 vcc, exec, s[60:61]
	s_cbranch_vccz .LBB0_112

; __device__ __forceinline__ unsigned xb_ld(unsigned* p)              { return __hip_atomic_load(p, __ATOMIC_RELAXED, __HIP_MEMORY_SCOPE_AGENT); }
; __device__ __forceinline__ void xcd_barrier_complete(unsigned* bar, unsigned x, unsigned& nloc, unsigned& nx) {
;     const unsigned G = gridDim.x * gridDim.y * gridDim.z;
;     unsigned sum, cnt, mine, sp = 0u;
;     for (;;) {
;         sum = 0u; cnt = 0u; mine = 0u;
; #pragma unroll
;         for (unsigned j = 0; j < 16; ++j) { const unsigned c = xb_ld(&bar[XB_XCNT(j)]); sum += c; cnt += (c > 0u) ? 1u : 0u; mine = (j == x) ? c : mine; }
;         if (sum == G) break;
;         __builtin_amdgcn_s_sleep(1);
;         if ((++sp & 255u) == 0u) { if (xb_ld(&bar[XB_TMO])) break; if (sp > XB_SPIN_CAP) { atomicAdd(&bar[XB_TMO], 1u); break; } }
;     }
;     nloc = mine > 0u ? mine : 1u; nx = cnt > 0u ? cnt : 1u;
; }
.LBB0_265:
	v_readlane_b32 s0, v247, 3
	v_readlane_b32 s1, v247, 4
	s_waitcnt lgkmcnt(0)
	global_load_dword v0, v193, s[58:59] sc1
	s_mov_b64 s[40:41], -1
	s_mov_b64 s[42:43], -1
	s_nop 0
	global_load_dword v1, v193, s[0:1] sc1
	v_readlane_b32 s0, v250, 35
	v_readlane_b32 s1, v250, 36
	s_waitcnt vmcnt(0)
	v_add_u32_e32 v16, v1, v0
	s_nop 2
	global_load_dword v2, v193, s[0:1] sc1
	v_readlane_b32 s0, v250, 37
	v_readlane_b32 s1, v250, 38
	s_waitcnt vmcnt(0)
	v_add_u32_e32 v16, v16, v2
	s_nop 2
	global_load_dword v3, v193, s[0:1] sc1
	v_readlane_b32 s0, v250, 39
	v_readlane_b32 s1, v250, 40
	s_waitcnt vmcnt(0)
	v_add_u32_e32 v16, v16, v3
	s_nop 2
	global_load_dword v4, v193, s[0:1] sc1
	v_readlane_b32 s0, v250, 41
	v_readlane_b32 s1, v250, 42
	s_waitcnt vmcnt(0)
	v_add_u32_e32 v16, v16, v4
	s_nop 2
	global_load_dword v5, v193, s[0:1] sc1
	v_readlane_b32 s0, v250, 43
	v_readlane_b32 s1, v250, 44
	s_waitcnt vmcnt(0)
	v_add_u32_e32 v16, v16, v5
	s_nop 2
	global_load_dword v6, v193, s[0:1] sc1
	v_readlane_b32 s0, v250, 45
	v_readlane_b32 s1, v250, 46
	s_waitcnt vmcnt(0)
	v_add_u32_e32 v16, v16, v6
	s_nop 2
	global_load_dword v7, v193, s[0:1] sc1
	v_readlane_b32 s0, v250, 47
	v_readlane_b32 s1, v250, 48
	s_waitcnt vmcnt(0)
	v_add_u32_e32 v16, v16, v7
	s_nop 2
	global_load_dword v8, v193, s[0:1] sc1
	v_readlane_b32 s0, v250, 49
	v_readlane_b32 s1, v250, 50
	s_waitcnt vmcnt(0)
	v_add_u32_e32 v16, v16, v8
	s_nop 2
	global_load_dword v9, v193, s[0:1] sc1
	v_readlane_b32 s0, v250, 51
	v_readlane_b32 s1, v250, 52
	s_waitcnt vmcnt(0)
	v_add_u32_e32 v16, v16, v9
	s_nop 2
	global_load_dword v10, v193, s[0:1] sc1
	v_readlane_b32 s0, v250, 53
	v_readlane_b32 s1, v250, 54
	s_waitcnt vmcnt(0)
	v_add_u32_e32 v16, v16, v10
	s_nop 2
	global_load_dword v11, v193, s[0:1] sc1
	v_readlane_b32 s0, v250, 55
	v_readlane_b32 s1, v250, 56
	s_waitcnt vmcnt(0)
	v_add_u32_e32 v16, v16, v11
	s_nop 2
	global_load_dword v12, v193, s[0:1] sc1
	v_readlane_b32 s0, v250, 57
	v_readlane_b32 s1, v250, 58
	s_waitcnt vmcnt(0)
	v_add_u32_e32 v16, v16, v12
	s_nop 2
	global_load_dword v13, v193, s[0:1] sc1
	v_readlane_b32 s0, v250, 59
	v_readlane_b32 s1, v250, 60
	s_waitcnt vmcnt(0)
	v_add_u32_e32 v16, v16, v13
	s_nop 2
	global_load_dword v14, v193, s[0:1] sc1
	v_readlane_b32 s0, v250, 61
	v_readlane_b32 s1, v250, 62
	s_waitcnt vmcnt(0)
	v_add_u32_e32 v16, v16, v14
	s_nop 2
	global_load_dword v15, v193, s[0:1] sc1
	s_waitcnt vmcnt(0)
	v_add_u32_e32 v16, v16, v15
	v_cmp_eq_u32_e32 vcc, s95, v16
	s_cbranch_vccnz .LBB0_264
	s_and_b32 s20, s19, 0xff
	s_cmp_eq_u32 s20, 0
	s_mov_b64 s[48:49], -1
	s_sleep 3
	s_cbranch_scc1 .LBB0_269
	s_and_b64 vcc, exec, s[48:49]
	s_cbranch_vccz .LBB0_264

; __device__ __forceinline__ unsigned xb_ld(unsigned* p)              { return __hip_atomic_load(p, __ATOMIC_RELAXED, __HIP_MEMORY_SCOPE_AGENT); }
; __device__ __forceinline__ unsigned xb_add(unsigned* p, unsigned v) { return __hip_atomic_fetch_add(p, v, __ATOMIC_RELAXED, __HIP_MEMORY_SCOPE_AGENT); }
; #define XB_SPIN(cond, bar) do { unsigned _sp = 0; while (cond) { __builtin_amdgcn_s_sleep(1); \
;     if ((++_sp & 255u) == 0u) { if (xb_ld(&(bar)[XB_TMO])) break; if (_sp > XB_SPIN_CAP) { atomicAdd(&(bar)[XB_TMO], 1u); break; } } } } while (0)
; __device__ __forceinline__ void xcd_barrier(const XcdBarrier& b) {
;     ...
;             else XB_SPIN(xb_ld(&bar[XB_TOPGEN]) == tg, bar);
;             __builtin_amdgcn_fence(__ATOMIC_ACQUIRE, "agent");
;             xb_add(&bar[XB_XGEN(b.x)], 1u);
;             asm volatile("s_waitcnt vmcnt(0)" ::: "memory");
;         } else {
;             XB_SPIN(xb_ld(&bar[XB_XGEN(b.x)]) == gen, bar);
.LBB0_283:
	s_and_b32 s20, s19, 0xff
	s_mov_b64 s[52:53], -1
	s_cmp_lg_u32 s20, 0
	s_mov_b64 s[56:57], -1
	s_sleep 3
	s_cbranch_scc0 .LBB0_286
	s_and_b64 vcc, exec, s[56:57]
	s_cbranch_vccz .LBB0_282

; __device__ __forceinline__ unsigned xb_ld(unsigned* p)              { return __hip_atomic_load(p, __ATOMIC_RELAXED, __HIP_MEMORY_SCOPE_AGENT); }
; __device__ __forceinline__ void xcd_barrier_complete(unsigned* bar, unsigned x, unsigned& nloc, unsigned& nx) {
;     const unsigned G = gridDim.x * gridDim.y * gridDim.z;
;     unsigned sum, cnt, mine, sp = 0u;
;     for (;;) {
;         sum = 0u; cnt = 0u; mine = 0u;
; #pragma unroll
;         for (unsigned j = 0; j < 16; ++j) { const unsigned c = xb_ld(&bar[XB_XCNT(j)]); sum += c; cnt += (c > 0u) ? 1u : 0u; mine = (j == x) ? c : mine; }
;         if (sum == G) break;
;         __builtin_amdgcn_s_sleep(1);
;         if ((++sp & 255u) == 0u) { if (xb_ld(&bar[XB_TMO])) break; if (sp > XB_SPIN_CAP) { atomicAdd(&bar[XB_TMO], 1u); break; } }
;     }
;     nloc = mine > 0u ? mine : 1u; nx = cnt > 0u ? cnt : 1u;
; }
.LBB0_576:
	v_readlane_b32 s0, v250, 35
	v_readlane_b32 s1, v250, 36
	global_load_dword v1, v193, s[58:59] sc1
	s_waitcnt lgkmcnt(0)
	global_load_dword v0, v193, s[72:73] sc1
	s_mov_b64 s[40:41], -1
	s_mov_b64 s[42:43], -1
	s_waitcnt vmcnt(0)
	v_add_u32_e32 v16, v0, v1
	global_load_dword v2, v193, s[0:1] sc1
	v_readlane_b32 s0, v250, 37
	v_readlane_b32 s1, v250, 38
	s_waitcnt vmcnt(0)
	v_add_u32_e32 v16, v16, v2
	s_nop 2
	global_load_dword v3, v193, s[0:1] sc1
	v_readlane_b32 s0, v250, 39
	v_readlane_b32 s1, v250, 40
	s_waitcnt vmcnt(0)
	v_add_u32_e32 v16, v16, v3
	s_nop 2
	global_load_dword v4, v193, s[0:1] sc1
	v_readlane_b32 s0, v250, 41
	v_readlane_b32 s1, v250, 42
	s_waitcnt vmcnt(0)
	v_add_u32_e32 v16, v16, v4
	s_nop 2
	global_load_dword v5, v193, s[0:1] sc1
	v_readlane_b32 s0, v250, 43
	v_readlane_b32 s1, v250, 44
	s_waitcnt vmcnt(0)
	v_add_u32_e32 v16, v16, v5
	s_nop 2
	global_load_dword v6, v193, s[0:1] sc1
	v_readlane_b32 s0, v250, 45
	v_readlane_b32 s1, v250, 46
	s_waitcnt vmcnt(0)
	v_add_u32_e32 v16, v16, v6
	s_nop 2
	global_load_dword v7, v193, s[0:1] sc1
	v_readlane_b32 s0, v250, 47
	v_readlane_b32 s1, v250, 48
	s_waitcnt vmcnt(0)
	v_add_u32_e32 v16, v16, v7
	s_nop 2
	global_load_dword v8, v193, s[0:1] sc1
	v_readlane_b32 s0, v250, 49
	v_readlane_b32 s1, v250, 50
	s_waitcnt vmcnt(0)
	v_add_u32_e32 v16, v16, v8
	s_nop 2
	global_load_dword v9, v193, s[0:1] sc1
	v_readlane_b32 s0, v250, 51
	v_readlane_b32 s1, v250, 52
	s_waitcnt vmcnt(0)
	v_add_u32_e32 v16, v16, v9
	s_nop 2
	global_load_dword v10, v193, s[0:1] sc1
	v_readlane_b32 s0, v250, 53
	v_readlane_b32 s1, v250, 54
	s_waitcnt vmcnt(0)
	v_add_u32_e32 v16, v16, v10
	s_nop 2
	global_load_dword v11, v193, s[0:1] sc1
	v_readlane_b32 s0, v250, 55
	v_readlane_b32 s1, v250, 56
	s_waitcnt vmcnt(0)
	v_add_u32_e32 v16, v16, v11
	s_nop 2
	global_load_dword v12, v193, s[0:1] sc1
	v_readlane_b32 s0, v250, 57
	v_readlane_b32 s1, v250, 58
	s_waitcnt vmcnt(0)
	v_add_u32_e32 v16, v16, v12
	s_nop 2
	global_load_dword v13, v193, s[0:1] sc1
	v_readlane_b32 s0, v250, 59
	v_readlane_b32 s1, v250, 60
	s_waitcnt vmcnt(0)
	v_add_u32_e32 v16, v16, v13
	s_nop 2
	global_load_dword v14, v193, s[0:1] sc1
	v_readlane_b32 s0, v250, 61
	v_readlane_b32 s1, v250, 62
	s_waitcnt vmcnt(0)
	v_add_u32_e32 v16, v16, v14
	s_nop 2
	global_load_dword v15, v193, s[0:1] sc1
	s_waitcnt vmcnt(0)
	v_add_u32_e32 v16, v16, v15
	v_cmp_eq_u32_e32 vcc, s95, v16
	s_cbranch_vccnz .LBB0_575
	s_and_b32 s20, s19, 0xff
	s_cmp_eq_u32 s20, 0
	s_mov_b64 s[44:45], -1
	s_sleep 3
	s_cbranch_scc1 .LBB0_580
	s_and_b64 vcc, exec, s[44:45]
	s_cbranch_vccz .LBB0_575

; __device__ __forceinline__ unsigned xb_ld(unsigned* p)              { return __hip_atomic_load(p, __ATOMIC_RELAXED, __HIP_MEMORY_SCOPE_AGENT); }
; __device__ __forceinline__ unsigned xb_add(unsigned* p, unsigned v) { return __hip_atomic_fetch_add(p, v, __ATOMIC_RELAXED, __HIP_MEMORY_SCOPE_AGENT); }
; #define XB_SPIN(cond, bar) do { unsigned _sp = 0; while (cond) { __builtin_amdgcn_s_sleep(1); \
;     if ((++_sp & 255u) == 0u) { if (xb_ld(&(bar)[XB_TMO])) break; if (_sp > XB_SPIN_CAP) { atomicAdd(&(bar)[XB_TMO], 1u); break; } } } } while (0)
; __device__ __forceinline__ void xcd_barrier(const XcdBarrier& b) {
;     ...
;             else XB_SPIN(xb_ld(&bar[XB_TOPGEN]) == tg, bar);
;             __builtin_amdgcn_fence(__ATOMIC_ACQUIRE, "agent");
;             xb_add(&bar[XB_XGEN(b.x)], 1u);
;             asm volatile("s_waitcnt vmcnt(0)" ::: "memory");
;         } else {
;             XB_SPIN(xb_ld(&bar[XB_XGEN(b.x)]) == gen, bar);
.LBB0_594:
	s_and_b32 s20, s19, 0xff
	s_mov_b64 s[48:49], -1
	s_cmp_lg_u32 s20, 0
	s_mov_b64 s[52:53], -1
	s_sleep 3
	s_cbranch_scc0 .LBB0_597
	s_and_b64 vcc, exec, s[52:53]
	s_cbranch_vccz .LBB0_593

; __device__ __forceinline__ unsigned xb_ld(unsigned* p)              { return __hip_atomic_load(p, __ATOMIC_RELAXED, __HIP_MEMORY_SCOPE_AGENT); }
; __device__ __forceinline__ void xcd_barrier_complete(unsigned* bar, unsigned x, unsigned& nloc, unsigned& nx) {
;     const unsigned G = gridDim.x * gridDim.y * gridDim.z;
;     unsigned sum, cnt, mine, sp = 0u;
;     for (;;) {
;         sum = 0u; cnt = 0u; mine = 0u;
; #pragma unroll
;         for (unsigned j = 0; j < 16; ++j) { const unsigned c = xb_ld(&bar[XB_XCNT(j)]); sum += c; cnt += (c > 0u) ? 1u : 0u; mine = (j == x) ? c : mine; }
;         if (sum == G) break;
;         __builtin_amdgcn_s_sleep(1);
;         if ((++sp & 255u) == 0u) { if (xb_ld(&bar[XB_TMO])) break; if (sp > XB_SPIN_CAP) { atomicAdd(&bar[XB_TMO], 1u); break; } }
;     }
;     nloc = mine > 0u ? mine : 1u; nx = cnt > 0u ? cnt : 1u;
; }
.LBB0_702:
	v_readlane_b32 s0, v250, 35
	v_readlane_b32 s1, v250, 36
	global_load_dword v1, v193, s[58:59] sc1
	s_waitcnt lgkmcnt(0)
	global_load_dword v0, v193, s[72:73] sc1
	s_mov_b64 s[42:43], -1
	s_mov_b64 s[44:45], -1
	s_waitcnt vmcnt(0)
	v_add_u32_e32 v16, v0, v1
	global_load_dword v2, v193, s[0:1] sc1
	v_readlane_b32 s0, v250, 37
	v_readlane_b32 s1, v250, 38
	s_waitcnt vmcnt(0)
	v_add_u32_e32 v16, v16, v2
	s_nop 2
	global_load_dword v3, v193, s[0:1] sc1
	v_readlane_b32 s0, v250, 39
	v_readlane_b32 s1, v250, 40
	s_waitcnt vmcnt(0)
	v_add_u32_e32 v16, v16, v3
	s_nop 2
	global_load_dword v4, v193, s[0:1] sc1
	v_readlane_b32 s0, v250, 41
	v_readlane_b32 s1, v250, 42
	s_waitcnt vmcnt(0)
	v_add_u32_e32 v16, v16, v4
	s_nop 2
	global_load_dword v5, v193, s[0:1] sc1
	v_readlane_b32 s0, v250, 43
	v_readlane_b32 s1, v250, 44
	s_waitcnt vmcnt(0)
	v_add_u32_e32 v16, v16, v5
	s_nop 2
	global_load_dword v6, v193, s[0:1] sc1
	v_readlane_b32 s0, v250, 45
	v_readlane_b32 s1, v250, 46
	s_waitcnt vmcnt(0)
	v_add_u32_e32 v16, v16, v6
	s_nop 2
	global_load_dword v7, v193, s[0:1] sc1
	v_readlane_b32 s0, v250, 47
	v_readlane_b32 s1, v250, 48
	s_waitcnt vmcnt(0)
	v_add_u32_e32 v16, v16, v7
	s_nop 2
	global_load_dword v8, v193, s[0:1] sc1
	v_readlane_b32 s0, v250, 49
	v_readlane_b32 s1, v250, 50
	s_waitcnt vmcnt(0)
	v_add_u32_e32 v16, v16, v8
	s_nop 2
	global_load_dword v9, v193, s[0:1] sc1
	v_readlane_b32 s0, v250, 51
	v_readlane_b32 s1, v250, 52
	s_waitcnt vmcnt(0)
	v_add_u32_e32 v16, v16, v9
	s_nop 2
	global_load_dword v10, v193, s[0:1] sc1
	v_readlane_b32 s0, v250, 53
	v_readlane_b32 s1, v250, 54
	s_waitcnt vmcnt(0)
	v_add_u32_e32 v16, v16, v10
	s_nop 2
	global_load_dword v11, v193, s[0:1] sc1
	v_readlane_b32 s0, v250, 55
	v_readlane_b32 s1, v250, 56
	s_waitcnt vmcnt(0)
	v_add_u32_e32 v16, v16, v11
	s_nop 2
	global_load_dword v12, v193, s[0:1] sc1
	v_readlane_b32 s0, v250, 57
	v_readlane_b32 s1, v250, 58
	s_waitcnt vmcnt(0)
	v_add_u32_e32 v16, v16, v12
	s_nop 2
	global_load_dword v13, v193, s[0:1] sc1
	v_readlane_b32 s0, v250, 59
	v_readlane_b32 s1, v250, 60
	s_waitcnt vmcnt(0)
	v_add_u32_e32 v16, v16, v13
	s_nop 2
	global_load_dword v14, v193, s[0:1] sc1
	v_readlane_b32 s0, v250, 61
	v_readlane_b32 s1, v250, 62
	s_waitcnt vmcnt(0)
	v_add_u32_e32 v16, v16, v14
	s_nop 2
	global_load_dword v15, v193, s[0:1] sc1
	s_waitcnt vmcnt(0)
	v_add_u32_e32 v16, v16, v15
	v_cmp_eq_u32_e32 vcc, s95, v16
	s_cbranch_vccnz .LBB0_701
	s_and_b32 s20, s19, 0xff
	s_cmp_eq_u32 s20, 0
	s_mov_b64 s[46:47], -1
	s_sleep 3
	s_cbranch_scc1 .LBB0_706
	s_and_b64 vcc, exec, s[46:47]
	s_cbranch_vccz .LBB0_701

; __device__ __forceinline__ unsigned xb_ld(unsigned* p)              { return __hip_atomic_load(p, __ATOMIC_RELAXED, __HIP_MEMORY_SCOPE_AGENT); }
; __device__ __forceinline__ unsigned xb_add(unsigned* p, unsigned v) { return __hip_atomic_fetch_add(p, v, __ATOMIC_RELAXED, __HIP_MEMORY_SCOPE_AGENT); }
; #define XB_SPIN(cond, bar) do { unsigned _sp = 0; while (cond) { __builtin_amdgcn_s_sleep(1); \
;     if ((++_sp & 255u) == 0u) { if (xb_ld(&(bar)[XB_TMO])) break; if (_sp > XB_SPIN_CAP) { atomicAdd(&(bar)[XB_TMO], 1u); break; } } } } while (0)
; __device__ __forceinline__ void xcd_barrier(const XcdBarrier& b) {
;     ...
;             else XB_SPIN(xb_ld(&bar[XB_TOPGEN]) == tg, bar);
;             __builtin_amdgcn_fence(__ATOMIC_ACQUIRE, "agent");
;             xb_add(&bar[XB_XGEN(b.x)], 1u);
;             asm volatile("s_waitcnt vmcnt(0)" ::: "memory");
;         } else {
;             XB_SPIN(xb_ld(&bar[XB_XGEN(b.x)]) == gen, bar);
.LBB0_720:
	s_and_b32 s20, s19, 0xff
	s_mov_b64 s[50:51], -1
	s_cmp_lg_u32 s20, 0
	s_mov_b64 s[54:55], -1
	s_sleep 3
	s_cbranch_scc0 .LBB0_723
	s_and_b64 vcc, exec, s[54:55]
	s_cbranch_vccz .LBB0_719
